# final RMSNorm: loop unrolled by two rows with a second register set, next row's loads issued before the current row's reduction
# baseline (speedup 1.0000x reference)
; #define TIDX tid_opaque()
; __device__ void rmsnorm_phase(const float* src, const float* g, float* copy_dst, bf16_t* xn, float* outf) {
;     const int lane = TIDX & 63, gw = blockIdx.x * 8 + (TIDX >> 6), nw = gridDim.x * 8;
;     f32x4 gv[4];
; #pragma unroll
;     for (int j = 0; j < 4; ++j) gv[j] = ((const f32x4*)g)[lane + 64 * j];
;     for (int row = gw; row < MT; row += nw) {
;         const f32x4* pr = (const f32x4*)(src + (size_t)row * DM); f32x4 v[4]; float ss = 0.f;
; #pragma unroll
;         for (int j = 0; j < 4; ++j) { v[j] = pr[lane + 64 * j]; ss += v[j][0] * v[j][0] + v[j][1] * v[j][1] + v[j][2] * v[j][2] + v[j][3] * v[j][3]; }
; __global__ void __launch_bounds__(512, 2) fwd_megakernel(Params p) {
;     ...
;         if (l == DEPTH) { rmsnorm_phase(h, ((const float*)ldp(36)), nullptr, nullptr, h); break; }
.LBB0_838:
	s_and_b64 vcc, exec, s[0:1]
	s_cbranch_vccz .LBB0_5
	s_add_i32 s0, 0, 0x23f20
	s_cmp_lg_u32 s0, -1
	s_cselect_b32 s0, s0, 0
	s_cselect_b32 s1, s41, 0
	s_waitcnt vmcnt(3)
	v_mov_b32_e32 v0, s0
	v_mov_b32_e32 v1, s1
	flat_load_dwordx2 v[2:3], v[0:1] sc0 sc1
	s_waitcnt vmcnt(0)
	v_mov_b32_e32 v0, v234
	v_mov_b32_e32 v1, v234
	s_mov_b32 s5, 0x8000
	v_ashrrev_i32_e32 v1, 6, v1
	v_add_u32_e32 v32, s77, v1
	v_cmp_gt_i32_e32 vcc, s5, v32
	s_waitcnt lgkmcnt(0)
	v_readfirstlane_b32 s1, v3
	v_readfirstlane_b32 s0, v2
	s_and_saveexec_b64 s[6:7], vcc
	s_cbranch_execz .LBB0_4
	v_lshlrev_b32_e32 v0, 4, v0
	v_and_b32_e32 v18, 0x3f0, v0
	s_nop 0
	global_load_dwordx4 v[0:3], v18, s[0:1]
	global_load_dwordx4 v[4:7], v18, s[0:1] offset:1024
	global_load_dwordx4 v[8:11], v18, s[0:1] offset:2048
	global_load_dwordx4 v[12:15], v18, s[0:1] offset:3072
	v_and_b32_e32 v16, 64, v243
	v_add_u32_e32 v16, 64, v16
	v_xor_b32_e32 v17, 32, v243
	v_cmp_lt_i32_e32 vcc, v17, v16
	v_readlane_b32 s0, v254, 19
	v_readlane_b32 s1, v254, 20
	v_cndmask_b32_e32 v17, v243, v17, vcc
	v_lshlrev_b32_e32 v36, 2, v17
	v_xor_b32_e32 v17, 16, v243
	v_cmp_lt_i32_e32 vcc, v17, v16
	s_load_dword s0, s[0:1], 0x0
	v_ashrrev_i32_e32 v33, 31, v32
	v_cndmask_b32_e32 v17, v243, v17, vcc
	v_lshlrev_b32_e32 v37, 2, v17
	v_xor_b32_e32 v17, 8, v243
	v_cmp_lt_i32_e32 vcc, v17, v16
	s_waitcnt lgkmcnt(0)
	s_lshl_b32 s8, s0, 3
	v_readlane_b32 s0, v255, 22
	v_cndmask_b32_e32 v17, v243, v17, vcc
	v_lshlrev_b32_e32 v38, 2, v17
	v_xor_b32_e32 v17, 4, v243
	v_cmp_lt_i32_e32 vcc, v17, v16
	v_readlane_b32 s1, v255, 23
	s_ashr_i32 s9, s8, 31
	v_cndmask_b32_e32 v17, v243, v17, vcc
	v_lshlrev_b32_e32 v39, 2, v17
	v_xor_b32_e32 v17, 2, v243
	v_cmp_lt_i32_e32 vcc, v17, v16
	s_lshl_b64 s[10:11], s[8:9], 12
	s_mov_b64 s[12:13], 0
	v_cndmask_b32_e32 v17, v243, v17, vcc
	v_lshlrev_b32_e32 v40, 2, v17
	v_xor_b32_e32 v17, 1, v243
	v_cmp_lt_i32_e32 vcc, v17, v16
	s_nop 1
	v_cndmask_b32_e32 v16, v243, v17, vcc
	v_lshlrev_b32_e32 v41, 2, v16
	v_lshlrev_b64 v[16:17], 12, v[32:33]
	v_or_b32_e32 v16, v16, v18
	v_lshl_add_u64 v[34:35], s[0:1], 0, v[16:17]
	global_load_dwordx4 v[28:31], v[34:35], off offset:-3072
	global_load_dwordx4 v[24:27], v[34:35], off offset:-2048
	global_load_dwordx4 v[20:23], v[34:35], off offset:-1024
	global_load_dwordx4 v[16:19], v[34:35], off
	s_branch .Lrn_A
.Lrn_A:
	v_add_u32_e32 v66, s8, v32
	v_cmp_ge_i32_e32 vcc, s88, v66
	s_cbranch_vccz .Lrn_A_np
	v_lshl_add_u64 v[64:65], v[34:35], 0, s[10:11]
	global_load_dwordx4 v[60:63], v[64:65], off offset:-3072
	global_load_dwordx4 v[56:59], v[64:65], off offset:-2048
	global_load_dwordx4 v[52:55], v[64:65], off offset:-1024
	global_load_dwordx4 v[48:51], v[64:65], off
	s_branch .Lrn_A_go

; __device__ __forceinline__ unsigned cvt_pk_bf16(float lo, float hi) { const f32x2_t v = {lo, hi}; const bf16x2_t b = __builtin_convertvector(v, bf16x2_t); return __builtin_bit_cast(unsigned, b); }
; __device__ void rmsnorm_phase(const float* src, const float* g, float* copy_dst, bf16_t* xn, float* outf) {
;     ...
;         for (int j = 0; j < 4; ++j) { v[j] = pr[lane + 64 * j]; ss += v[j][0] * v[j][0] + v[j][1] * v[j][1] + v[j][2] * v[j][2] + v[j][3] * v[j][3]; }
; #pragma unroll
;         for (int o = 32; o >= 1; o >>= 1) ss += __shfl_xor(ss, o);
;         const float r = 1.0f / sqrtf(ss * (1.0f / DM) + 1e-6f);
; #pragma unroll
;         for (int j = 0; j < 4; ++j) { const f32x4 y = v[j] * r * gv[j];
;             if (copy_dst) ((f32x4*)(copy_dst + (size_t)row * DM))[lane + 64 * j] = v[j];
;             if (xn) { u32x2 w; w.x = cvt_pk_bf16(y[0], y[1]); w.y = cvt_pk_bf16(y[2], y[3]); ((u32x2*)(xn + (size_t)row * DM))[lane + 64 * j] = w; }
;             if (outf) ((f32x4*)(outf + (size_t)row * DM))[lane + 64 * j] = y; }
.Lrn_A_go:
	s_andn2_b64 vcc, exec, s[86:87]
	s_waitcnt vmcnt(7)
	v_mul_f32_e32 v33, v29, v29
	s_waitcnt vmcnt(6) lgkmcnt(0)
	v_mul_f32_e32 v42, v25, v25
	s_waitcnt vmcnt(5)
	v_mul_f32_e32 v43, v21, v21
	v_fmac_f32_e32 v33, v28, v28
	v_fmac_f32_e32 v42, v24, v24
	s_waitcnt vmcnt(4)
	v_mul_f32_e32 v44, v17, v17
	v_fmac_f32_e32 v43, v20, v20
	v_fmac_f32_e32 v33, v30, v30
	v_fmac_f32_e32 v42, v26, v26
	v_fmac_f32_e32 v44, v16, v16
	v_fmac_f32_e32 v43, v22, v22
	v_fmac_f32_e32 v33, v31, v31
	v_fmac_f32_e32 v42, v27, v27
	v_fmac_f32_e32 v44, v18, v18
	v_fmac_f32_e32 v43, v23, v23
	v_add_f32_e32 v33, v33, v42
	v_add_f32_e32 v33, v33, v43
	v_fmac_f32_e32 v44, v19, v19
	v_add_f32_e32 v33, v33, v44
	ds_bpermute_b32 v42, v36, v33
	s_waitcnt lgkmcnt(0)
	v_add_f32_e32 v33, v33, v42
	ds_bpermute_b32 v42, v37, v33
	s_waitcnt lgkmcnt(0)
	v_add_f32_e32 v33, v33, v42
	ds_bpermute_b32 v42, v38, v33
	s_waitcnt lgkmcnt(0)
	v_add_f32_e32 v33, v33, v42
	ds_bpermute_b32 v42, v39, v33
	s_waitcnt lgkmcnt(0)
	v_add_f32_e32 v33, v33, v42
	ds_bpermute_b32 v42, v40, v33
	s_waitcnt lgkmcnt(0)
	v_add_f32_e32 v33, v33, v42
	ds_bpermute_b32 v42, v41, v33
	s_cbranch_vccnz .Lrn_A_lt
	s_waitcnt lgkmcnt(0)
	v_add_f32_e32 v33, v33, v42
	v_fmamk_f32 v33, v33, 0x3a800000, v235
	s_mov_b32 s0, 0xf800000
	v_mul_f32_e32 v42, 0x4f800000, v33
	v_cmp_gt_f32_e32 vcc, s0, v33
	s_nop 1
	v_cndmask_b32_e32 v33, v33, v42, vcc
	v_sqrt_f32_e32 v42, v33
	s_nop 0
	v_add_u32_e32 v43, -1, v42
	v_fma_f32 v45, -v43, v42, v33
	v_add_u32_e32 v44, 1, v42
	v_cmp_ge_f32_e64 s[0:1], 0, v45
	s_nop 1
	v_cndmask_b32_e64 v43, v42, v43, s[0:1]
	v_fma_f32 v42, -v44, v42, v33
	v_cmp_lt_f32_e64 s[0:1], 0, v42
	s_nop 1
	v_cndmask_b32_e64 v42, v43, v44, s[0:1]
	v_mul_f32_e32 v43, 0x37800000, v42
	v_cndmask_b32_e32 v42, v42, v43, vcc
	v_cmp_class_f32_e32 vcc, v33, v236
	s_nop 1
	v_cndmask_b32_e32 v33, v42, v33, vcc
	v_div_scale_f32 v42, s[0:1], v33, v33, 1.0
	v_rcp_f32_e32 v43, v42
	s_nop 0
	v_fma_f32 v44, -v42, v43, 1.0
	v_fmac_f32_e32 v43, v44, v43
	v_div_scale_f32 v44, vcc, 1.0, v33, 1.0
	v_mul_f32_e32 v45, v44, v43
	v_fma_f32 v46, -v42, v45, v44
	v_fmac_f32_e32 v45, v46, v43
	v_fma_f32 v42, -v42, v45, v44
	v_div_fmas_f32 v42, v42, v43, v45
	v_div_fixup_f32 v42, v42, v33, 1.0
	v_pk_mul_f32 v[28:29], v[28:29], v[42:43] op_sel_hi:[1,0]
	v_pk_mul_f32 v[30:31], v[30:31], v[42:43] op_sel_hi:[1,0]
	v_pk_mul_f32 v[24:25], v[24:25], v[42:43] op_sel_hi:[1,0]
	v_pk_mul_f32 v[26:27], v[26:27], v[42:43] op_sel_hi:[1,0]
	v_pk_mul_f32 v[20:21], v[20:21], v[42:43] op_sel_hi:[1,0]
	v_pk_mul_f32 v[22:23], v[22:23], v[42:43] op_sel_hi:[1,0]
	v_pk_mul_f32 v[16:17], v[16:17], v[42:43] op_sel_hi:[1,0]
	v_pk_mul_f32 v[18:19], v[18:19], v[42:43] op_sel_hi:[1,0]
	v_pk_mul_f32 v[30:31], v[2:3], v[30:31]
	v_pk_mul_f32 v[28:29], v[0:1], v[28:29]
	v_pk_mul_f32 v[26:27], v[6:7], v[26:27]
	v_pk_mul_f32 v[24:25], v[4:5], v[24:25]
	v_pk_mul_f32 v[22:23], v[10:11], v[22:23]
	v_pk_mul_f32 v[20:21], v[8:9], v[20:21]
	v_pk_mul_f32 v[18:19], v[14:15], v[18:19]
	v_pk_mul_f32 v[16:17], v[12:13], v[16:17]
	global_store_dwordx4 v[34:35], v[28:31], off offset:-3072
	global_store_dwordx4 v[34:35], v[24:27], off offset:-2048
	global_store_dwordx4 v[34:35], v[20:23], off offset:-1024
	global_store_dwordx4 v[34:35], v[16:19], off

; __device__ void rmsnorm_phase(const float* src, const float* g, float* copy_dst, bf16_t* xn, float* outf) {
;     ...
;     for (int row = gw; row < MT; row += nw) {
;         const f32x4* pr = (const f32x4*)(src + (size_t)row * DM); f32x4 v[4]; float ss = 0.f;
.Lrn_B:
	v_add_u32_e32 v66, s8, v32
	v_cmp_ge_i32_e32 vcc, s88, v66
	s_cbranch_vccz .Lrn_B_np
	v_lshl_add_u64 v[64:65], v[34:35], 0, s[10:11]
	global_load_dwordx4 v[28:31], v[64:65], off offset:-3072
	global_load_dwordx4 v[24:27], v[64:65], off offset:-2048
	global_load_dwordx4 v[20:23], v[64:65], off offset:-1024
	global_load_dwordx4 v[16:19], v[64:65], off
	s_branch .Lrn_B_go

; __device__ __forceinline__ unsigned cvt_pk_bf16(float lo, float hi) { const f32x2_t v = {lo, hi}; const bf16x2_t b = __builtin_convertvector(v, bf16x2_t); return __builtin_bit_cast(unsigned, b); }
; __device__ void rmsnorm_phase(const float* src, const float* g, float* copy_dst, bf16_t* xn, float* outf) {
;     ...
;         for (int j = 0; j < 4; ++j) { v[j] = pr[lane + 64 * j]; ss += v[j][0] * v[j][0] + v[j][1] * v[j][1] + v[j][2] * v[j][2] + v[j][3] * v[j][3]; }
; #pragma unroll
;         for (int o = 32; o >= 1; o >>= 1) ss += __shfl_xor(ss, o);
;         const float r = 1.0f / sqrtf(ss * (1.0f / DM) + 1e-6f);
; #pragma unroll
;         for (int j = 0; j < 4; ++j) { const f32x4 y = v[j] * r * gv[j];
;             if (copy_dst) ((f32x4*)(copy_dst + (size_t)row * DM))[lane + 64 * j] = v[j];
;             if (xn) { u32x2 w; w.x = cvt_pk_bf16(y[0], y[1]); w.y = cvt_pk_bf16(y[2], y[3]); ((u32x2*)(xn + (size_t)row * DM))[lane + 64 * j] = w; }
;             if (outf) ((f32x4*)(outf + (size_t)row * DM))[lane + 64 * j] = y; }
;     }
.Lrn_B_go:
	s_andn2_b64 vcc, exec, s[86:87]
	s_waitcnt vmcnt(7)
	v_mul_f32_e32 v33, v61, v61
	s_waitcnt vmcnt(6) lgkmcnt(0)
	v_mul_f32_e32 v42, v57, v57
	s_waitcnt vmcnt(5)
	v_mul_f32_e32 v43, v53, v53
	v_fmac_f32_e32 v33, v60, v60
	v_fmac_f32_e32 v42, v56, v56
	s_waitcnt vmcnt(4)
	v_mul_f32_e32 v44, v49, v49
	v_fmac_f32_e32 v43, v52, v52
	v_fmac_f32_e32 v33, v62, v62
	v_fmac_f32_e32 v42, v58, v58
	v_fmac_f32_e32 v44, v48, v48
	v_fmac_f32_e32 v43, v54, v54
	v_fmac_f32_e32 v33, v63, v63
	v_fmac_f32_e32 v42, v59, v59
	v_fmac_f32_e32 v44, v50, v50
	v_fmac_f32_e32 v43, v55, v55
	v_add_f32_e32 v33, v33, v42
	v_add_f32_e32 v33, v33, v43
	v_fmac_f32_e32 v44, v51, v51
	v_add_f32_e32 v33, v33, v44
	ds_bpermute_b32 v42, v36, v33
	s_waitcnt lgkmcnt(0)
	v_add_f32_e32 v33, v33, v42
	ds_bpermute_b32 v42, v37, v33
	s_waitcnt lgkmcnt(0)
	v_add_f32_e32 v33, v33, v42
	ds_bpermute_b32 v42, v38, v33
	s_waitcnt lgkmcnt(0)
	v_add_f32_e32 v33, v33, v42
	ds_bpermute_b32 v42, v39, v33
	s_waitcnt lgkmcnt(0)
	v_add_f32_e32 v33, v33, v42
	ds_bpermute_b32 v42, v40, v33
	s_waitcnt lgkmcnt(0)
	v_add_f32_e32 v33, v33, v42
	ds_bpermute_b32 v42, v41, v33
	s_cbranch_vccnz .Lrn_B_lt
	s_waitcnt lgkmcnt(0)
	v_add_f32_e32 v33, v33, v42
	v_fmamk_f32 v33, v33, 0x3a800000, v235
	s_mov_b32 s0, 0xf800000
	v_mul_f32_e32 v42, 0x4f800000, v33
	v_cmp_gt_f32_e32 vcc, s0, v33
	s_nop 1
	v_cndmask_b32_e32 v33, v33, v42, vcc
	v_sqrt_f32_e32 v42, v33
	s_nop 0
	v_add_u32_e32 v43, -1, v42
	v_fma_f32 v45, -v43, v42, v33
	v_add_u32_e32 v44, 1, v42
	v_cmp_ge_f32_e64 s[0:1], 0, v45
	s_nop 1
	v_cndmask_b32_e64 v43, v42, v43, s[0:1]
	v_fma_f32 v42, -v44, v42, v33
	v_cmp_lt_f32_e64 s[0:1], 0, v42
	s_nop 1
	v_cndmask_b32_e64 v42, v43, v44, s[0:1]
	v_mul_f32_e32 v43, 0x37800000, v42
	v_cndmask_b32_e32 v42, v42, v43, vcc
	v_cmp_class_f32_e32 vcc, v33, v236
	s_nop 1
	v_cndmask_b32_e32 v33, v42, v33, vcc
	v_div_scale_f32 v42, s[0:1], v33, v33, 1.0
	v_rcp_f32_e32 v43, v42
	s_nop 0
	v_fma_f32 v44, -v42, v43, 1.0
	v_fmac_f32_e32 v43, v44, v43
	v_div_scale_f32 v44, vcc, 1.0, v33, 1.0
	v_mul_f32_e32 v45, v44, v43
	v_fma_f32 v46, -v42, v45, v44
	v_fmac_f32_e32 v45, v46, v43
	v_fma_f32 v42, -v42, v45, v44
	v_div_fmas_f32 v42, v42, v43, v45
	v_div_fixup_f32 v42, v42, v33, 1.0
	v_pk_mul_f32 v[60:61], v[60:61], v[42:43] op_sel_hi:[1,0]
	v_pk_mul_f32 v[62:63], v[62:63], v[42:43] op_sel_hi:[1,0]
	v_pk_mul_f32 v[56:57], v[56:57], v[42:43] op_sel_hi:[1,0]
	v_pk_mul_f32 v[58:59], v[58:59], v[42:43] op_sel_hi:[1,0]
	v_pk_mul_f32 v[52:53], v[52:53], v[42:43] op_sel_hi:[1,0]
	v_pk_mul_f32 v[54:55], v[54:55], v[42:43] op_sel_hi:[1,0]
	v_pk_mul_f32 v[48:49], v[48:49], v[42:43] op_sel_hi:[1,0]
	v_pk_mul_f32 v[50:51], v[50:51], v[42:43] op_sel_hi:[1,0]
	v_pk_mul_f32 v[62:63], v[2:3], v[62:63]
	v_pk_mul_f32 v[60:61], v[0:1], v[60:61]
	v_pk_mul_f32 v[58:59], v[6:7], v[58:59]
	v_pk_mul_f32 v[56:57], v[4:5], v[56:57]
	v_pk_mul_f32 v[54:55], v[10:11], v[54:55]
	v_pk_mul_f32 v[52:53], v[8:9], v[52:53]
	v_pk_mul_f32 v[50:51], v[14:15], v[50:51]
	v_pk_mul_f32 v[48:49], v[12:13], v[48:49]
	global_store_dwordx4 v[34:35], v[60:63], off offset:-3072
	global_store_dwordx4 v[34:35], v[56:59], off offset:-2048
	global_store_dwordx4 v[34:35], v[52:55], off offset:-1024
	global_store_dwordx4 v[34:35], v[48:51], off
.Lrn_B_lt:
	v_add_u32_e32 v32, s8, v32
	v_cmp_lt_i32_e32 vcc, s88, v32
	s_or_b64 s[12:13], vcc, s[12:13]
	v_lshl_add_u64 v[34:35], v[34:35], 0, s[10:11]
	s_andn2_b64 exec, exec, s[12:13]
	s_cbranch_execz .LBB0_4
	s_branch .Lrn_A
